# PV MFMA order k-step-major: consecutive MFMAs accumulate into different O blocks (no back-to-back dependent MFMAs)
# speedup vs baseline: 1.0089x; 1.0022x over previous
.LBB0_517:
	v_cndmask_b32_e64 v231, v234, v231, s[4:5]
	v_mul_f32_e32 v192, 0xbe0293ee, v231
	v_fmamk_f32 v144, v144, 0x3e0293ee, v192
	v_fmamk_f32 v145, v145, 0x3e0293ee, v192
	v_fmamk_f32 v146, v146, 0x3e0293ee, v192
	v_fmamk_f32 v147, v147, 0x3e0293ee, v192
	v_fmamk_f32 v148, v148, 0x3e0293ee, v192
	v_fmamk_f32 v149, v149, 0x3e0293ee, v192
	v_fmamk_f32 v150, v150, 0x3e0293ee, v192
	v_fmamk_f32 v151, v151, 0x3e0293ee, v192
	v_fmamk_f32 v152, v152, 0x3e0293ee, v192
	v_fmamk_f32 v153, v153, 0x3e0293ee, v192
	v_fmamk_f32 v154, v154, 0x3e0293ee, v192
	v_fmamk_f32 v155, v155, 0x3e0293ee, v192
	v_fmamk_f32 v156, v156, 0x3e0293ee, v192
	v_fmamk_f32 v157, v157, 0x3e0293ee, v192
	v_fmamk_f32 v158, v158, 0x3e0293ee, v192
	v_fmamk_f32 v159, v159, 0x3e0293ee, v192
	v_fmamk_f32 v128, v128, 0x3e0293ee, v192
	v_fmamk_f32 v129, v129, 0x3e0293ee, v192
	v_fmamk_f32 v130, v130, 0x3e0293ee, v192
	v_fmamk_f32 v131, v131, 0x3e0293ee, v192
	v_fmamk_f32 v132, v132, 0x3e0293ee, v192
	v_fmamk_f32 v133, v133, 0x3e0293ee, v192
	v_fmamk_f32 v134, v134, 0x3e0293ee, v192
	v_fmamk_f32 v135, v135, 0x3e0293ee, v192
	v_fmamk_f32 v136, v136, 0x3e0293ee, v192
	v_fmamk_f32 v137, v137, 0x3e0293ee, v192
	v_fmamk_f32 v138, v138, 0x3e0293ee, v192
	v_fmamk_f32 v139, v139, 0x3e0293ee, v192
	v_fmamk_f32 v140, v140, 0x3e0293ee, v192
	v_fmamk_f32 v141, v141, 0x3e0293ee, v192
	v_fmamk_f32 v142, v142, 0x3e0293ee, v192
	v_fmac_f32_e32 v192, 0x3e0293ee, v143
	v_exp_f32_e32 v143, v144
	v_exp_f32_e32 v145, v145
	v_exp_f32_e32 v146, v146
	v_exp_f32_e32 v147, v147
	v_exp_f32_e32 v148, v148
	v_exp_f32_e32 v193, v128
	v_exp_f32_e32 v149, v149
	v_add_f32_e32 v128, v145, v143
	v_exp_f32_e32 v150, v150
	v_add_f32_e32 v128, v146, v128
	v_exp_f32_e32 v151, v151
	v_add_f32_e32 v128, v147, v128
	v_exp_f32_e32 v152, v152
	v_add_f32_e32 v128, v148, v128
	v_exp_f32_e32 v153, v153
	v_add_f32_e32 v128, v149, v128
	v_exp_f32_e32 v154, v154
	v_add_f32_e32 v128, v150, v128
	v_exp_f32_e32 v155, v155
	v_add_f32_e32 v128, v151, v128
	v_exp_f32_e32 v156, v156
	v_add_f32_e32 v128, v152, v128
	v_exp_f32_e32 v157, v157
	v_add_f32_e32 v128, v153, v128
	v_exp_f32_e32 v158, v158
	v_add_f32_e32 v128, v154, v128
	v_exp_f32_e32 v159, v159
	v_add_f32_e32 v128, v155, v128
	v_add_f32_e32 v128, v156, v128
	v_exp_f32_e32 v194, v129
	v_add_f32_e32 v128, v157, v128
	v_exp_f32_e32 v195, v130
	v_add_f32_e32 v128, v158, v128
	v_exp_f32_e32 v196, v131
	v_add_f32_e32 v128, v159, v128
	v_exp_f32_e32 v197, v132
	v_add_f32_e32 v128, v193, v128
	v_exp_f32_e32 v198, v133
	v_add_f32_e32 v128, v194, v128
	v_exp_f32_e32 v199, v134
	v_add_f32_e32 v128, v195, v128
	v_exp_f32_e32 v135, v135
	v_add_f32_e32 v128, v196, v128
	v_exp_f32_e32 v200, v136
	v_add_f32_e32 v128, v197, v128
	v_exp_f32_e32 v201, v137
	v_add_f32_e32 v128, v198, v128
	v_exp_f32_e32 v202, v138
	v_add_f32_e32 v128, v199, v128
	v_exp_f32_e32 v203, v139
	v_add_f32_e32 v128, v135, v128
	v_exp_f32_e32 v204, v140
	v_add_f32_e32 v128, v200, v128
	v_exp_f32_e32 v205, v141
	v_add_f32_e32 v128, v201, v128
	v_exp_f32_e32 v206, v142
	v_add_f32_e32 v128, v202, v128
	v_exp_f32_e32 v192, v192
	v_add_f32_e32 v128, v203, v128
	v_add_f32_e32 v128, v204, v128
	v_add_f32_e32 v128, v205, v128
	v_add_f32_e32 v128, v206, v128
	v_add_f32_e32 v128, v192, v128
	v_mov_b32_e32 v129, v128
	s_nop 1
	v_permlane32_swap_b32_e32 v128, v129
	v_add_f32_e32 v144, v128, v129
	v_fmac_f32_e32 v144, v232, v233
	v_cvt_pk_bf16_f32 v128, v143, v145
	v_cvt_pk_bf16_f32 v129, v146, v147
	v_cvt_pk_bf16_f32 v130, v148, v149
	v_cvt_pk_bf16_f32 v131, v150, v151
	v_cvt_pk_bf16_f32 v136, v152, v153
	v_cvt_pk_bf16_f32 v137, v154, v155
	v_cvt_pk_bf16_f32 v138, v156, v157
	v_cvt_pk_bf16_f32 v139, v158, v159
	v_cvt_pk_bf16_f32 v132, v193, v194
	v_cvt_pk_bf16_f32 v133, v195, v196
	v_cvt_pk_bf16_f32 v134, v197, v198
	v_cvt_pk_bf16_f32 v135, v199, v135
	v_cvt_pk_bf16_f32 v140, v200, v201
	v_cvt_pk_bf16_f32 v141, v202, v203
	v_cvt_pk_bf16_f32 v142, v204, v205
	v_cvt_pk_bf16_f32 v143, v206, v192
	v_lshl_add_u32 v145, s76, 15, v230
	ds_read_b64_tr_b16 v[146:147], v145 offset:0
	ds_read_b64_tr_b16 v[148:149], v145 offset:4096
	ds_read_b64_tr_b16 v[150:151], v145 offset:512
	ds_read_b64_tr_b16 v[152:153], v145 offset:4608
	ds_read_b64_tr_b16 v[154:155], v145 offset:1024
	ds_read_b64_tr_b16 v[156:157], v145 offset:5120
	ds_read_b64_tr_b16 v[192:193], v145 offset:1536
	ds_read_b64_tr_b16 v[194:195], v145 offset:5632
	ds_read_b64_tr_b16 v[196:197], v145 offset:2048
	ds_read_b64_tr_b16 v[198:199], v145 offset:6144
	ds_read_b64_tr_b16 v[200:201], v145 offset:2560
	ds_read_b64_tr_b16 v[202:203], v145 offset:6656
	ds_read_b64_tr_b16 v[204:205], v145 offset:3072
	ds_read_b64_tr_b16 v[206:207], v145 offset:7168
	s_waitcnt lgkmcnt(12)
	s_nop 0
	v_mfma_f32_32x32x16_bf16 v[0:15], v[128:131], v[146:149], v[0:15]
	ds_read_b64_tr_b16 v[232:233], v145 offset:3584
	ds_read_b64_tr_b16 v[234:235], v145 offset:7680
	s_waitcnt lgkmcnt(12)
	v_mfma_f32_32x32x16_bf16 v[112:127], v[128:131], v[150:153], v[112:127]
	ds_read_b64_tr_b16 v[146:147], v145 offset:8192
	ds_read_b64_tr_b16 v[148:149], v145 offset:12288
	s_waitcnt lgkmcnt(12)
	v_mfma_f32_32x32x16_bf16 v[96:111], v[128:131], v[154:157], v[96:111]
	ds_read_b64_tr_b16 v[150:151], v145 offset:8704
	ds_read_b64_tr_b16 v[152:153], v145 offset:12800
	s_waitcnt lgkmcnt(12)
	v_mfma_f32_32x32x16_bf16 v[80:95], v[128:131], v[192:195], v[80:95]
	ds_read_b64_tr_b16 v[154:155], v145 offset:9216
	ds_read_b64_tr_b16 v[156:157], v145 offset:13312
	s_waitcnt lgkmcnt(12)
	v_mfma_f32_32x32x16_bf16 v[64:79], v[128:131], v[196:199], v[64:79]
	ds_read_b64_tr_b16 v[192:193], v145 offset:9728
	ds_read_b64_tr_b16 v[194:195], v145 offset:13824
	s_waitcnt lgkmcnt(12)
	v_mfma_f32_32x32x16_bf16 v[48:63], v[128:131], v[200:203], v[48:63]
	ds_read_b64_tr_b16 v[196:197], v145 offset:10240
	ds_read_b64_tr_b16 v[198:199], v145 offset:14336
	s_waitcnt lgkmcnt(12)
	v_mfma_f32_32x32x16_bf16 v[32:47], v[128:131], v[204:207], v[32:47]
	ds_read_b64_tr_b16 v[200:201], v145 offset:10752
	ds_read_b64_tr_b16 v[202:203], v145 offset:14848
	s_waitcnt lgkmcnt(12)
	v_mfma_f32_32x32x16_bf16 v[16:31], v[128:131], v[232:235], v[16:31]
	ds_read_b64_tr_b16 v[204:205], v145 offset:11264
	ds_read_b64_tr_b16 v[206:207], v145 offset:15360
	s_waitcnt lgkmcnt(12)
	v_mfma_f32_32x32x16_bf16 v[0:15], v[136:139], v[146:149], v[0:15]
	ds_read_b64_tr_b16 v[232:233], v145 offset:11776
	ds_read_b64_tr_b16 v[234:235], v145 offset:15872
	s_waitcnt lgkmcnt(12)
	v_mfma_f32_32x32x16_bf16 v[112:127], v[136:139], v[150:153], v[112:127]
	ds_read_b64_tr_b16 v[146:147], v145 offset:16384
	ds_read_b64_tr_b16 v[148:149], v145 offset:20480
	s_waitcnt lgkmcnt(12)
	v_mfma_f32_32x32x16_bf16 v[96:111], v[136:139], v[154:157], v[96:111]
	ds_read_b64_tr_b16 v[150:151], v145 offset:16896
	ds_read_b64_tr_b16 v[152:153], v145 offset:20992
	s_waitcnt lgkmcnt(12)
	v_mfma_f32_32x32x16_bf16 v[80:95], v[136:139], v[192:195], v[80:95]
	ds_read_b64_tr_b16 v[154:155], v145 offset:17408
	ds_read_b64_tr_b16 v[156:157], v145 offset:21504
	s_waitcnt lgkmcnt(12)
	v_mfma_f32_32x32x16_bf16 v[64:79], v[136:139], v[196:199], v[64:79]
	ds_read_b64_tr_b16 v[192:193], v145 offset:17920
	ds_read_b64_tr_b16 v[194:195], v145 offset:22016
	s_waitcnt lgkmcnt(12)
	v_mfma_f32_32x32x16_bf16 v[48:63], v[136:139], v[200:203], v[48:63]
	ds_read_b64_tr_b16 v[196:197], v145 offset:18432
	ds_read_b64_tr_b16 v[198:199], v145 offset:22528
	s_waitcnt lgkmcnt(12)
	v_mfma_f32_32x32x16_bf16 v[32:47], v[136:139], v[204:207], v[32:47]
	ds_read_b64_tr_b16 v[200:201], v145 offset:18944
	ds_read_b64_tr_b16 v[202:203], v145 offset:23040
	s_waitcnt lgkmcnt(12)
	v_mfma_f32_32x32x16_bf16 v[16:31], v[136:139], v[232:235], v[16:31]
	ds_read_b64_tr_b16 v[204:205], v145 offset:19456
	ds_read_b64_tr_b16 v[206:207], v145 offset:23552
	s_waitcnt lgkmcnt(12)
	v_mfma_f32_32x32x16_bf16 v[0:15], v[132:135], v[146:149], v[0:15]
	ds_read_b64_tr_b16 v[232:233], v145 offset:19968
	ds_read_b64_tr_b16 v[234:235], v145 offset:24064
	s_waitcnt lgkmcnt(12)
	v_mfma_f32_32x32x16_bf16 v[112:127], v[132:135], v[150:153], v[112:127]
	ds_read_b64_tr_b16 v[146:147], v145 offset:24576
	ds_read_b64_tr_b16 v[148:149], v145 offset:28672
	s_waitcnt lgkmcnt(12)
	v_mfma_f32_32x32x16_bf16 v[96:111], v[132:135], v[154:157], v[96:111]
	ds_read_b64_tr_b16 v[150:151], v145 offset:25088
	ds_read_b64_tr_b16 v[152:153], v145 offset:29184
	s_waitcnt lgkmcnt(12)
	v_mfma_f32_32x32x16_bf16 v[80:95], v[132:135], v[192:195], v[80:95]
	ds_read_b64_tr_b16 v[154:155], v145 offset:25600
	ds_read_b64_tr_b16 v[156:157], v145 offset:29696
	s_waitcnt lgkmcnt(12)
	v_mfma_f32_32x32x16_bf16 v[64:79], v[132:135], v[196:199], v[64:79]
	ds_read_b64_tr_b16 v[192:193], v145 offset:26112
	ds_read_b64_tr_b16 v[194:195], v145 offset:30208
	s_waitcnt lgkmcnt(12)
	v_mfma_f32_32x32x16_bf16 v[48:63], v[132:135], v[200:203], v[48:63]
	ds_read_b64_tr_b16 v[196:197], v145 offset:26624
	ds_read_b64_tr_b16 v[198:199], v145 offset:30720
	s_waitcnt lgkmcnt(12)
	v_mfma_f32_32x32x16_bf16 v[32:47], v[132:135], v[204:207], v[32:47]
	ds_read_b64_tr_b16 v[200:201], v145 offset:27136
	ds_read_b64_tr_b16 v[202:203], v145 offset:31232
	s_waitcnt lgkmcnt(12)
	v_mfma_f32_32x32x16_bf16 v[16:31], v[132:135], v[232:235], v[16:31]
	ds_read_b64_tr_b16 v[204:205], v145 offset:27648
	ds_read_b64_tr_b16 v[206:207], v145 offset:31744
	s_waitcnt lgkmcnt(12)
	v_mfma_f32_32x32x16_bf16 v[0:15], v[140:143], v[146:149], v[0:15]
	ds_read_b64_tr_b16 v[232:233], v145 offset:28160
	ds_read_b64_tr_b16 v[234:235], v145 offset:32256
	s_waitcnt lgkmcnt(12)
	v_mfma_f32_32x32x16_bf16 v[112:127], v[140:143], v[150:153], v[112:127]
	s_waitcnt lgkmcnt(10)
	v_mfma_f32_32x32x16_bf16 v[96:111], v[140:143], v[154:157], v[96:111]
	s_waitcnt lgkmcnt(8)
	v_mfma_f32_32x32x16_bf16 v[80:95], v[140:143], v[192:195], v[80:95]
	s_waitcnt lgkmcnt(6)
	v_mfma_f32_32x32x16_bf16 v[64:79], v[140:143], v[196:199], v[64:79]
	s_add_i32 s4, s76, 1
	s_cmp_lg_u32 s76, 2
	s_cselect_b32 s76, s4, 0
	s_add_i32 s4, s74, 1
	s_cmp_lg_u32 s74, 2
	s_cselect_b32 s74, s4, 0
	s_add_u32 s22, s22, 0x20000
	s_waitcnt lgkmcnt(4)
	v_mfma_f32_32x32x16_bf16 v[48:63], v[140:143], v[200:203], v[48:63]
	s_addc_u32 s23, s23, 0
	s_add_i32 s86, s86, 1
	s_cmp_eq_u32 s22, 0x800000
	s_waitcnt lgkmcnt(2)
	v_mfma_f32_32x32x16_bf16 v[32:47], v[140:143], v[204:207], v[32:47]
	s_waitcnt lgkmcnt(0)
	v_mfma_f32_32x32x16_bf16 v[16:31], v[140:143], v[232:235], v[16:31]
	s_cbranch_scc1 .LBB0_521
	v_mov_b32_e32 v232, v144
	s_cmp_eq_u32 s22, 0x7e0000
	s_mov_b64 s[4:5], -1
	s_cbranch_scc1 .LBB0_510

.LBB0_910:
	v_cndmask_b32_e64 v231, v234, v231, s[4:5]
	v_mul_f32_e32 v192, 0xbe0293ee, v231
	v_fmamk_f32 v144, v144, 0x3e0293ee, v192
	v_fmamk_f32 v145, v145, 0x3e0293ee, v192
	v_fmamk_f32 v146, v146, 0x3e0293ee, v192
	v_fmamk_f32 v147, v147, 0x3e0293ee, v192
	v_fmamk_f32 v148, v148, 0x3e0293ee, v192
	v_fmamk_f32 v149, v149, 0x3e0293ee, v192
	v_fmamk_f32 v150, v150, 0x3e0293ee, v192
	v_fmamk_f32 v151, v151, 0x3e0293ee, v192
	v_fmamk_f32 v152, v152, 0x3e0293ee, v192
	v_fmamk_f32 v153, v153, 0x3e0293ee, v192
	v_fmamk_f32 v154, v154, 0x3e0293ee, v192
	v_fmamk_f32 v155, v155, 0x3e0293ee, v192
	v_fmamk_f32 v156, v156, 0x3e0293ee, v192
	v_fmamk_f32 v157, v157, 0x3e0293ee, v192
	v_fmamk_f32 v158, v158, 0x3e0293ee, v192
	v_fmamk_f32 v159, v159, 0x3e0293ee, v192
	v_fmamk_f32 v128, v128, 0x3e0293ee, v192
	v_fmamk_f32 v129, v129, 0x3e0293ee, v192
	v_fmamk_f32 v130, v130, 0x3e0293ee, v192
	v_fmamk_f32 v131, v131, 0x3e0293ee, v192
	v_fmamk_f32 v132, v132, 0x3e0293ee, v192
	v_fmamk_f32 v133, v133, 0x3e0293ee, v192
	v_fmamk_f32 v134, v134, 0x3e0293ee, v192
	v_fmamk_f32 v135, v135, 0x3e0293ee, v192
	v_fmamk_f32 v136, v136, 0x3e0293ee, v192
	v_fmamk_f32 v137, v137, 0x3e0293ee, v192
	v_fmamk_f32 v138, v138, 0x3e0293ee, v192
	v_fmamk_f32 v139, v139, 0x3e0293ee, v192
	v_fmamk_f32 v140, v140, 0x3e0293ee, v192
	v_fmamk_f32 v141, v141, 0x3e0293ee, v192
	v_fmamk_f32 v142, v142, 0x3e0293ee, v192
	v_fmac_f32_e32 v192, 0x3e0293ee, v143
	v_exp_f32_e32 v143, v144
	v_exp_f32_e32 v145, v145
	v_exp_f32_e32 v146, v146
	v_exp_f32_e32 v147, v147
	v_exp_f32_e32 v148, v148
	v_exp_f32_e32 v193, v128
	v_exp_f32_e32 v149, v149
	v_add_f32_e32 v128, v145, v143
	v_exp_f32_e32 v150, v150
	v_add_f32_e32 v128, v146, v128
	v_exp_f32_e32 v151, v151
	v_add_f32_e32 v128, v147, v128
	v_exp_f32_e32 v152, v152
	v_add_f32_e32 v128, v148, v128
	v_exp_f32_e32 v153, v153
	v_add_f32_e32 v128, v149, v128
	v_exp_f32_e32 v154, v154
	v_add_f32_e32 v128, v150, v128
	v_exp_f32_e32 v155, v155
	v_add_f32_e32 v128, v151, v128
	v_exp_f32_e32 v156, v156
	v_add_f32_e32 v128, v152, v128
	v_exp_f32_e32 v157, v157
	v_add_f32_e32 v128, v153, v128
	v_exp_f32_e32 v158, v158
	v_add_f32_e32 v128, v154, v128
	v_exp_f32_e32 v159, v159
	v_add_f32_e32 v128, v155, v128
	v_add_f32_e32 v128, v156, v128
	v_exp_f32_e32 v194, v129
	v_add_f32_e32 v128, v157, v128
	v_exp_f32_e32 v195, v130
	v_add_f32_e32 v128, v158, v128
	v_exp_f32_e32 v196, v131
	v_add_f32_e32 v128, v159, v128
	v_exp_f32_e32 v197, v132
	v_add_f32_e32 v128, v193, v128
	v_exp_f32_e32 v198, v133
	v_add_f32_e32 v128, v194, v128
	v_exp_f32_e32 v199, v134
	v_add_f32_e32 v128, v195, v128
	v_exp_f32_e32 v135, v135
	v_add_f32_e32 v128, v196, v128
	v_exp_f32_e32 v200, v136
	v_add_f32_e32 v128, v197, v128
	v_exp_f32_e32 v201, v137
	v_add_f32_e32 v128, v198, v128
	v_exp_f32_e32 v202, v138
	v_add_f32_e32 v128, v199, v128
	v_exp_f32_e32 v203, v139
	v_add_f32_e32 v128, v135, v128
	v_exp_f32_e32 v204, v140
	v_add_f32_e32 v128, v200, v128
	v_exp_f32_e32 v205, v141
	v_add_f32_e32 v128, v201, v128
	v_exp_f32_e32 v206, v142
	v_add_f32_e32 v128, v202, v128
	v_exp_f32_e32 v192, v192
	v_add_f32_e32 v128, v203, v128
	v_add_f32_e32 v128, v204, v128
	v_add_f32_e32 v128, v205, v128
	v_add_f32_e32 v128, v206, v128
	v_add_f32_e32 v128, v192, v128
	v_mov_b32_e32 v129, v128
	s_nop 1
	v_permlane32_swap_b32_e32 v128, v129
	v_add_f32_e32 v144, v128, v129
	v_fmac_f32_e32 v144, v232, v233
	v_cvt_pk_bf16_f32 v128, v143, v145
	v_cvt_pk_bf16_f32 v129, v146, v147
	v_cvt_pk_bf16_f32 v130, v148, v149
	v_cvt_pk_bf16_f32 v131, v150, v151
	v_cvt_pk_bf16_f32 v136, v152, v153
	v_cvt_pk_bf16_f32 v137, v154, v155
	v_cvt_pk_bf16_f32 v138, v156, v157
	v_cvt_pk_bf16_f32 v139, v158, v159
	v_cvt_pk_bf16_f32 v132, v193, v194
	v_cvt_pk_bf16_f32 v133, v195, v196
	v_cvt_pk_bf16_f32 v134, v197, v198
	v_cvt_pk_bf16_f32 v135, v199, v135
	v_cvt_pk_bf16_f32 v140, v200, v201
	v_cvt_pk_bf16_f32 v141, v202, v203
	v_cvt_pk_bf16_f32 v142, v204, v205
	v_cvt_pk_bf16_f32 v143, v206, v192
	v_lshl_add_u32 v145, s80, 15, v230
	ds_read_b64_tr_b16 v[146:147], v145 offset:0
	ds_read_b64_tr_b16 v[148:149], v145 offset:4096
	ds_read_b64_tr_b16 v[150:151], v145 offset:512
	ds_read_b64_tr_b16 v[152:153], v145 offset:4608
	ds_read_b64_tr_b16 v[154:155], v145 offset:1024
	ds_read_b64_tr_b16 v[156:157], v145 offset:5120
	ds_read_b64_tr_b16 v[192:193], v145 offset:1536
	ds_read_b64_tr_b16 v[194:195], v145 offset:5632
	ds_read_b64_tr_b16 v[196:197], v145 offset:2048
	ds_read_b64_tr_b16 v[198:199], v145 offset:6144
	ds_read_b64_tr_b16 v[200:201], v145 offset:2560
	ds_read_b64_tr_b16 v[202:203], v145 offset:6656
	ds_read_b64_tr_b16 v[204:205], v145 offset:3072
	ds_read_b64_tr_b16 v[206:207], v145 offset:7168
	s_waitcnt lgkmcnt(12)
	s_nop 0
	v_mfma_f32_32x32x16_bf16 v[0:15], v[128:131], v[146:149], v[0:15]
	ds_read_b64_tr_b16 v[232:233], v145 offset:3584
	ds_read_b64_tr_b16 v[234:235], v145 offset:7680
	s_waitcnt lgkmcnt(12)
	v_mfma_f32_32x32x16_bf16 v[112:127], v[128:131], v[150:153], v[112:127]
	ds_read_b64_tr_b16 v[146:147], v145 offset:8192
	ds_read_b64_tr_b16 v[148:149], v145 offset:12288
	s_waitcnt lgkmcnt(12)
	v_mfma_f32_32x32x16_bf16 v[96:111], v[128:131], v[154:157], v[96:111]
	ds_read_b64_tr_b16 v[150:151], v145 offset:8704
	ds_read_b64_tr_b16 v[152:153], v145 offset:12800
	s_waitcnt lgkmcnt(12)
	v_mfma_f32_32x32x16_bf16 v[80:95], v[128:131], v[192:195], v[80:95]
	ds_read_b64_tr_b16 v[154:155], v145 offset:9216
	ds_read_b64_tr_b16 v[156:157], v145 offset:13312
	s_waitcnt lgkmcnt(12)
	v_mfma_f32_32x32x16_bf16 v[64:79], v[128:131], v[196:199], v[64:79]
	ds_read_b64_tr_b16 v[192:193], v145 offset:9728
	ds_read_b64_tr_b16 v[194:195], v145 offset:13824
	s_waitcnt lgkmcnt(12)
	v_mfma_f32_32x32x16_bf16 v[48:63], v[128:131], v[200:203], v[48:63]
	ds_read_b64_tr_b16 v[196:197], v145 offset:10240
	ds_read_b64_tr_b16 v[198:199], v145 offset:14336
	s_waitcnt lgkmcnt(12)
	v_mfma_f32_32x32x16_bf16 v[32:47], v[128:131], v[204:207], v[32:47]
	ds_read_b64_tr_b16 v[200:201], v145 offset:10752
	ds_read_b64_tr_b16 v[202:203], v145 offset:14848
	s_waitcnt lgkmcnt(12)
	v_mfma_f32_32x32x16_bf16 v[16:31], v[128:131], v[232:235], v[16:31]
	ds_read_b64_tr_b16 v[204:205], v145 offset:11264
	ds_read_b64_tr_b16 v[206:207], v145 offset:15360
	s_waitcnt lgkmcnt(12)
	v_mfma_f32_32x32x16_bf16 v[0:15], v[136:139], v[146:149], v[0:15]
	ds_read_b64_tr_b16 v[232:233], v145 offset:11776
	ds_read_b64_tr_b16 v[234:235], v145 offset:15872
	s_waitcnt lgkmcnt(12)
	v_mfma_f32_32x32x16_bf16 v[112:127], v[136:139], v[150:153], v[112:127]
	ds_read_b64_tr_b16 v[146:147], v145 offset:16384
	ds_read_b64_tr_b16 v[148:149], v145 offset:20480
	s_waitcnt lgkmcnt(12)
	v_mfma_f32_32x32x16_bf16 v[96:111], v[136:139], v[154:157], v[96:111]
	ds_read_b64_tr_b16 v[150:151], v145 offset:16896
	ds_read_b64_tr_b16 v[152:153], v145 offset:20992
	s_waitcnt lgkmcnt(12)
	v_mfma_f32_32x32x16_bf16 v[80:95], v[136:139], v[192:195], v[80:95]
	ds_read_b64_tr_b16 v[154:155], v145 offset:17408
	ds_read_b64_tr_b16 v[156:157], v145 offset:21504
	s_waitcnt lgkmcnt(12)
	v_mfma_f32_32x32x16_bf16 v[64:79], v[136:139], v[196:199], v[64:79]
	ds_read_b64_tr_b16 v[192:193], v145 offset:17920
	ds_read_b64_tr_b16 v[194:195], v145 offset:22016
	s_waitcnt lgkmcnt(12)
	v_mfma_f32_32x32x16_bf16 v[48:63], v[136:139], v[200:203], v[48:63]
	ds_read_b64_tr_b16 v[196:197], v145 offset:18432
	ds_read_b64_tr_b16 v[198:199], v145 offset:22528
	s_waitcnt lgkmcnt(12)
	v_mfma_f32_32x32x16_bf16 v[32:47], v[136:139], v[204:207], v[32:47]
	ds_read_b64_tr_b16 v[200:201], v145 offset:18944
	ds_read_b64_tr_b16 v[202:203], v145 offset:23040
	s_waitcnt lgkmcnt(12)
	v_mfma_f32_32x32x16_bf16 v[16:31], v[136:139], v[232:235], v[16:31]
	ds_read_b64_tr_b16 v[204:205], v145 offset:19456
	ds_read_b64_tr_b16 v[206:207], v145 offset:23552
	s_waitcnt lgkmcnt(12)
	v_mfma_f32_32x32x16_bf16 v[0:15], v[132:135], v[146:149], v[0:15]
	ds_read_b64_tr_b16 v[232:233], v145 offset:19968
	ds_read_b64_tr_b16 v[234:235], v145 offset:24064
	s_waitcnt lgkmcnt(12)
	v_mfma_f32_32x32x16_bf16 v[112:127], v[132:135], v[150:153], v[112:127]
	ds_read_b64_tr_b16 v[146:147], v145 offset:24576
	ds_read_b64_tr_b16 v[148:149], v145 offset:28672
	s_waitcnt lgkmcnt(12)
	v_mfma_f32_32x32x16_bf16 v[96:111], v[132:135], v[154:157], v[96:111]
	ds_read_b64_tr_b16 v[150:151], v145 offset:25088
	ds_read_b64_tr_b16 v[152:153], v145 offset:29184
	s_waitcnt lgkmcnt(12)
	v_mfma_f32_32x32x16_bf16 v[80:95], v[132:135], v[192:195], v[80:95]
	ds_read_b64_tr_b16 v[154:155], v145 offset:25600
	ds_read_b64_tr_b16 v[156:157], v145 offset:29696
	s_waitcnt lgkmcnt(12)
	v_mfma_f32_32x32x16_bf16 v[64:79], v[132:135], v[196:199], v[64:79]
	ds_read_b64_tr_b16 v[192:193], v145 offset:26112
	ds_read_b64_tr_b16 v[194:195], v145 offset:30208
	s_waitcnt lgkmcnt(12)
	v_mfma_f32_32x32x16_bf16 v[48:63], v[132:135], v[200:203], v[48:63]
	ds_read_b64_tr_b16 v[196:197], v145 offset:26624
	ds_read_b64_tr_b16 v[198:199], v145 offset:30720
	s_waitcnt lgkmcnt(12)
	v_mfma_f32_32x32x16_bf16 v[32:47], v[132:135], v[204:207], v[32:47]
	ds_read_b64_tr_b16 v[200:201], v145 offset:27136
	ds_read_b64_tr_b16 v[202:203], v145 offset:31232
	s_waitcnt lgkmcnt(12)
	v_mfma_f32_32x32x16_bf16 v[16:31], v[132:135], v[232:235], v[16:31]
	ds_read_b64_tr_b16 v[204:205], v145 offset:27648
	ds_read_b64_tr_b16 v[206:207], v145 offset:31744
	s_waitcnt lgkmcnt(12)
	v_mfma_f32_32x32x16_bf16 v[0:15], v[140:143], v[146:149], v[0:15]
	ds_read_b64_tr_b16 v[232:233], v145 offset:28160
	ds_read_b64_tr_b16 v[234:235], v145 offset:32256
	s_waitcnt lgkmcnt(12)
	v_mfma_f32_32x32x16_bf16 v[112:127], v[140:143], v[150:153], v[112:127]
	s_waitcnt lgkmcnt(10)
	v_mfma_f32_32x32x16_bf16 v[96:111], v[140:143], v[154:157], v[96:111]
	s_waitcnt lgkmcnt(8)
	v_mfma_f32_32x32x16_bf16 v[80:95], v[140:143], v[192:195], v[80:95]
	s_waitcnt lgkmcnt(6)
	v_mfma_f32_32x32x16_bf16 v[64:79], v[140:143], v[196:199], v[64:79]
	s_add_i32 s4, s80, 1
	s_cmp_lg_u32 s80, 2
	s_cselect_b32 s80, s4, 0
	s_add_i32 s4, s78, 1
	s_cmp_lg_u32 s78, 2
	s_cselect_b32 s78, s4, 0
	s_add_u32 s22, s22, 0x20000
	s_waitcnt lgkmcnt(4)
	v_mfma_f32_32x32x16_bf16 v[48:63], v[140:143], v[200:203], v[48:63]
	s_addc_u32 s23, s23, 0
	s_add_i32 s86, s86, 1
	s_cmp_eq_u32 s22, 0x800000
	s_waitcnt lgkmcnt(2)
	v_mfma_f32_32x32x16_bf16 v[32:47], v[140:143], v[204:207], v[32:47]
	s_waitcnt lgkmcnt(0)
	v_mfma_f32_32x32x16_bf16 v[16:31], v[140:143], v[232:235], v[16:31]
	s_cbranch_scc1 .LBB0_914
	v_mov_b32_e32 v232, v144
	s_cmp_eq_u32 s22, 0x7e0000
	s_mov_b64 s[4:5], -1
	s_cbranch_scc1 .LBB0_903
